# grid barrier: the middle arriver of each XCD issues an extra early L2 write-back so the release write-back has less to flush
# baseline (speedup 1.0000x reference)
; __device__ __forceinline__ unsigned xb_ld(unsigned* p)              { return __hip_atomic_load(p, __ATOMIC_RELAXED, __HIP_MEMORY_SCOPE_AGENT); }
; __device__ __forceinline__ unsigned xb_add(unsigned* p, unsigned v) { return __hip_atomic_fetch_add(p, v, __ATOMIC_RELAXED, __HIP_MEMORY_SCOPE_AGENT); }
; #define XB_SPIN(cond, bar) do { unsigned _sp = 0; while (cond) { __builtin_amdgcn_s_sleep(1); \
;     if ((++_sp & 255u) == 0u) { if (xb_ld(&(bar)[XB_TMO])) break; if (_sp > XB_SPIN_CAP) { atomicAdd(&(bar)[XB_TMO], 1u); break; } } } } while (0)
; __device__ __forceinline__ void xcd_barrier(const XcdBarrier& b) {
;     ...
;         unsigned nloc = b.st[0], nx = b.st[1];
;         if (nloc == 0u) { xcd_barrier_complete(bar, b.x, nloc, nx); b.st[0] = nloc; b.st[1] = nx; }
;         const unsigned old = xb_add(&bar[XB_XSUB(b.x)], 1u);
;         const unsigned gen = old / nloc;
;         if (old + 1u == (gen + 1u) * nloc) {
;             __builtin_amdgcn_fence(__ATOMIC_RELEASE, "agent");
;             asm volatile("s_waitcnt vmcnt(0)" ::: "memory");
;             const unsigned og = xb_add(&bar[XB_TOP], 1u);
;             const unsigned tg = og / nx;
;             if (og + 1u == (tg + 1u) * nx) xb_add(&bar[XB_TOPGEN], 1u);
;             else XB_SPIN(xb_ld(&bar[XB_TOPGEN]) == tg, bar);
;             __builtin_amdgcn_fence(__ATOMIC_ACQUIRE, "agent");
;             xb_add(&bar[XB_XGEN(b.x)], 1u);
;             asm volatile("s_waitcnt vmcnt(0)" ::: "memory");
;         } else {
;             XB_SPIN(xb_ld(&bar[XB_XGEN(b.x)]) == gen, bar);
.LBB0_963:
	s_or_b64 exec, exec, s[2:3]
	v_cvt_f32_u32_e32 v5, v3
	s_waitcnt vmcnt(0)
	v_readfirstlane_b32 s2, v4
	v_sub_u32_e32 v4, 0, v3
	v_rcp_iflag_f32_e32 v5, v5
	v_add_u32_e32 v6, s2, v0
	v_mul_f32_e32 v5, 0x4f7ffffe, v5
	v_cvt_u32_f32_e32 v5, v5
	v_mul_lo_u32 v0, v4, v5
	v_mul_hi_u32 v0, v5, v0
	v_add_u32_e32 v0, v5, v0
	v_mul_hi_u32 v0, v6, v0
	v_mul_lo_u32 v4, v0, v3
	v_sub_u32_e32 v4, v6, v4
	v_add_u32_e32 v5, 1, v0
	v_cmp_ge_u32_e32 vcc, v4, v3
	s_nop 1
	v_cndmask_b32_e32 v0, v0, v5, vcc
	v_sub_u32_e32 v5, v4, v3
	v_cndmask_b32_e32 v4, v4, v5, vcc
	v_lshrrev_b32_e32 v5, 1, v3
	v_cmp_ne_u32_e32 vcc, v4, v5
	s_cbranch_vccnz .Lbar_nomid
	buffer_wbl2 sc1
.Lbar_nomid:
	v_add_u32_e32 v5, 1, v0
	v_cmp_ge_u32_e32 vcc, v4, v3
	v_add_u32_e32 v4, 1, v6
	s_nop 0
	v_cndmask_b32_e32 v0, v0, v5, vcc
	v_mul_lo_u32 v5, v3, v0
	v_add_u32_e32 v3, v5, v3
	v_cmp_ne_u32_e32 vcc, v4, v3
	s_and_saveexec_b64 s[2:3], vcc
	s_xor_b64 s[2:3], exec, s[2:3]
	s_cbranch_execz .LBB0_977
	v_readlane_b32 s4, v254, 53
	v_readlane_b32 s5, v254, 54
	s_waitcnt lgkmcnt(0)
	s_nop 3
	global_load_dword v2, v1, s[4:5] sc1
	s_waitcnt vmcnt(0)
	v_cmp_eq_u32_e32 vcc, v2, v0
	s_and_saveexec_b64 s[4:5], vcc
	s_cbranch_execz .LBB0_976
	s_mov_b32 s11, 1
	s_mov_b64 s[6:7], 0
	s_branch .LBB0_967
